# static s_setprio 1 for waves 4-7 during the prompt attention units (reset before HGRN pass 1)
# speedup vs baseline: 1.0260x; 1.0260x over previous
.LBB0_310:
	s_or_b64 exec, exec, s[0:1]
	s_add_u32 s10, s72, 0xdb00000
	s_addc_u32 s11, s73, 0
	s_add_i32 s0, 0, 0x20028
	v_mov_b32_e32 v1, s0
	s_waitcnt lgkmcnt(0)
	s_barrier
	ds_read_b64 v[2:3], v1
	v_and_b32_e32 v1, 63, v183
	s_mov_b32 s15, 0
	v_writelane_b32 v254, s55, 30
	s_waitcnt lgkmcnt(0)
	v_readfirstlane_b32 s18, v2
	s_cmpk_gt_i32 s18, 0x1ff
	v_readfirstlane_b32 s34, v3
	s_cbranch_scc1 .LBB0_419
	s_add_u32 s35, s72, 0x4100000
	s_addc_u32 s36, s73, 0
	s_add_u32 s37, s72, 0x5200000
	s_addc_u32 s38, s73, 0
	s_add_u32 s39, s72, 0xf200000
	s_addc_u32 s40, s73, 0
	s_add_u32 s41, s72, 0x6300000
	s_addc_u32 s42, s73, 0
	s_add_u32 s43, s72, 0x10000000
	s_addc_u32 s48, s73, 0
	v_lshl_or_b32 v184, v1, 6, 63
	v_mov_b32_e32 v179, 0
	v_mov_b32_e32 v185, 0x10000
	v_mov_b32_e32 v186, 0x260
	s_movk_i32 s49, 0x7fff
	v_mov_b32_e32 v187, 0x3f80
	s_mov_b32 s52, 0x5040100
	s_mov_b32 s53, 0x41000000
	v_mov_b32_e32 v188, 0xff800000
	s_mov_b32 s70, 0
	v_mov_b32_e32 v189, 0
	v_readfirstlane_b32 s98, v0
	s_lshr_b32 s98, s98, 8
	s_cmp_eq_u32 s98, 0
	s_cbranch_scc1 .Lprio_skip
	s_setprio 1
.Lprio_skip:
	s_branch .LBB0_313
	s_nop 0
	s_nop 0
	s_nop 0
	s_nop 0
	s_nop 0
	s_nop 0
	s_nop 0
	s_nop 0
	s_nop 0
	s_nop 0
	s_nop 0
	s_nop 0
	s_nop 0
	s_nop 0
	s_nop 0
	s_nop 0
	s_nop 0
	s_nop 0
	s_nop 0
	s_nop 0
	s_nop 0
	s_nop 0
	s_nop 0
	s_nop 0
	s_nop 0
	s_nop 0
	s_nop 0
	s_nop 0
	s_nop 0
	s_nop 0
	s_nop 0
	s_nop 0
	s_nop 0
	s_nop 0
	s_nop 0
	s_nop 0
	s_nop 0
	s_nop 0
	s_nop 0
	s_nop 0
	s_nop 0
	s_nop 0
	s_nop 0
	s_nop 0
	s_nop 0
	s_nop 0
	s_nop 0
	s_nop 0
	s_nop 0
	s_nop 0
	s_nop 0
	s_nop 0
	s_nop 0
	s_nop 0
	s_nop 0
	s_nop 0
	s_nop 0
	s_nop 0
	s_nop 0

.LBB0_416:
	v_max_f32_e32 v67, v67, v67
	v_max_f32_e32 v68, 0, v67
	v_exp_f32_e64 v67, -v68
	s_and_saveexec_b64 s[6:7], s[4:5]
	ds_write_b32 v196, v67 offset:55296
	s_or_b64 exec, exec, s[6:7]
	v_sub_f32_e32 v65, v65, v68
	v_sub_f32_e32 v64, v64, v68
	v_sub_f32_e32 v63, v63, v68
	v_sub_f32_e32 v62, v62, v68
	v_sub_f32_e32 v61, v61, v68
	v_sub_f32_e32 v60, v60, v68
	v_sub_f32_e32 v59, v59, v68
	v_sub_f32_e32 v58, v58, v68
	v_sub_f32_e32 v57, v57, v68
	v_sub_f32_e32 v56, v56, v68
	v_sub_f32_e32 v55, v55, v68
	v_sub_f32_e32 v54, v54, v68
	v_sub_f32_e32 v53, v53, v68
	v_sub_f32_e32 v52, v52, v68
	v_sub_f32_e32 v51, v51, v68
	v_sub_f32_e32 v50, v50, v68
	v_sub_f32_e32 v49, v49, v68
	v_sub_f32_e32 v48, v48, v68
	v_sub_f32_e32 v47, v47, v68
	v_sub_f32_e32 v46, v46, v68
	v_sub_f32_e32 v45, v45, v68
	v_sub_f32_e32 v44, v44, v68
	v_sub_f32_e32 v43, v43, v68
	v_sub_f32_e32 v42, v42, v68
	v_sub_f32_e32 v41, v41, v68
	v_sub_f32_e32 v40, v40, v68
	v_sub_f32_e32 v39, v39, v68
	v_sub_f32_e32 v38, v38, v68
	v_sub_f32_e32 v37, v37, v68
	v_sub_f32_e32 v36, v36, v68
	v_sub_f32_e32 v35, v35, v68
	v_sub_f32_e32 v34, v34, v68
	v_mul_f32_e32 v66, v66, v67
	s_branch .LBB0_410
	s_nop 0
	s_nop 0
	s_nop 0
	s_nop 0
	s_nop 0
	s_nop 0
	s_nop 0
	s_nop 0
	s_nop 0
	s_nop 0
	s_nop 0
	s_nop 0
	s_nop 0
	s_nop 0
	s_nop 0
	s_nop 0
	s_nop 0
	s_nop 0
	s_nop 0
	s_nop 0
	s_nop 0
	s_nop 0
	s_nop 0
	s_nop 0
	s_nop 0
	s_nop 0
	s_nop 0
	s_nop 0
	s_nop 0
	s_nop 0
	s_nop 0
	s_nop 0
	s_nop 0
	s_nop 0
	s_nop 0
	s_nop 0
	s_nop 0
	s_nop 0
	s_nop 0
	s_nop 0
	s_nop 0
	s_nop 0
	s_nop 0
	s_nop 0
	s_nop 0
	s_nop 0
	s_nop 0
	s_nop 0
	s_nop 0
	s_nop 0
	s_nop 0
	s_nop 0
	s_nop 0
	s_nop 0
	s_nop 0
	s_nop 0
	s_nop 0
	s_nop 0
	s_nop 0
	s_nop 0
	s_nop 0
	s_nop 0
	s_nop 0
.LBB0_419:
	s_setprio 0
	s_mul_i32 s33, s95, 24
	v_readlane_b32 s0, v254, 21
	s_add_i32 s33, s33, s0
	v_readfirstlane_b32 s0, v0
	s_lshl_b32 s1, s33, 3
	s_lshr_b32 s0, s0, 6
	s_add_i32 s1, s0, s1
	s_cmp_gt_i32 s1, 15
	s_cbranch_scc1 .LBB0_421
	s_ashr_i32 s1, s1, 3
	s_and_b32 s2, s0, 7
	s_mul_hi_i32 s0, s1, 0x2080
	s_mulk_i32 s1, 0x2080
	v_and_b32_e32 v32, 31, v183
	s_or_b32 s4, s1, 0x60
	v_or_b32_e32 v40, s4, v32
	v_mov_b32_e32 v41, s0
	v_lshlrev_b64 v[6:7], 10, v[40:41]
	v_lshrrev_b32_e32 v16, 5, v1
	v_lshl_add_u64 v[2:3], s[8:9], 0, v[6:7]
	s_lshl_b32 s0, s2, 7
	s_mov_b32 s1, 0
	v_lshlrev_b64 v[8:9], 5, v[40:41]
	v_lshl_add_u64 v[6:7], s[72:73], 0, v[6:7]
	v_lshlrev_b32_e32 v22, 4, v16
	v_mov_b32_e32 v23, 0
	v_lshl_add_u64 v[8:9], s[10:11], 0, v[8:9]
	s_lshl_b32 s2, s2, 2
	s_mov_b32 s3, s1
	v_lshl_add_u64 v[6:7], v[6:7], 0, s[0:1]
	v_lshl_add_u64 v[12:13], v[8:9], 0, s[2:3]
	v_lshl_add_u64 v[14:15], v[6:7], 0, v[22:23]
	s_mov_b32 s3, 0x4100000
	v_lshl_add_u64 v[2:3], v[2:3], 0, s[0:1]
	v_add_co_u32_e32 v6, vcc, s3, v14
	v_lshl_add_u64 v[10:11], v[2:3], 0, v[22:23]
	s_nop 0
	v_addc_co_u32_e32 v7, vcc, 0, v15, vcc
	global_load_dwordx4 v[2:5], v[10:11], off
	global_load_dwordx4 v[24:27], v[10:11], off offset:32
	global_load_dwordx4 v[28:31], v[10:11], off offset:64
	s_mov_b64 s[6:7], 0x4100000
	global_load_dwordx4 v[6:9], v[6:7], off
	v_lshl_add_u64 v[14:15], v[14:15], 0, s[6:7]
	global_load_dword v62, v[12:13], off
	global_load_dwordx4 v[50:53], v[14:15], off offset:32
	global_load_dwordx4 v[54:57], v[14:15], off offset:64
	global_load_dwordx4 v[18:21], v[14:15], off offset:96
	v_lshlrev_b32_e32 v33, 2, v16
	v_or_b32_e32 v107, 16, v33
	s_add_u32 s2, s10, s2
	v_or_b32_e32 v40, s4, v107
	v_or_b32_e32 v106, 17, v33
	v_or_b32_e32 v105, 18, v33
	s_addc_u32 s3, s11, 0
	v_lshlrev_b64 v[12:13], 5, v[40:41]
	v_or_b32_e32 v48, s4, v106
	v_mov_b32_e32 v49, v41
	v_or_b32_e32 v44, s4, v105
	v_mov_b32_e32 v45, v41
	v_lshl_add_u64 v[12:13], s[2:3], 0, v[12:13]
	v_lshlrev_b64 v[14:15], 5, v[48:49]
	v_lshlrev_b64 v[16:17], 5, v[44:45]
	v_lshl_add_u64 v[14:15], s[2:3], 0, v[14:15]
	v_lshl_add_u64 v[16:17], s[2:3], 0, v[16:17]
	global_load_dword v63, v[12:13], off
	global_load_dword v64, v[14:15], off
	global_load_dword v65, v[16:17], off
	global_load_dwordx4 v[58:61], v[10:11], off offset:96
	v_or_b32_e32 v104, 19, v33
	v_or_b32_e32 v46, s4, v104
	v_mov_b32_e32 v47, v41
	v_lshlrev_b64 v[10:11], 5, v[46:47]
	v_or_b32_e32 v103, 24, v33
	v_lshl_add_u64 v[10:11], s[2:3], 0, v[10:11]
	global_load_dword v66, v[10:11], off
	v_or_b32_e32 v42, s4, v103
	v_mov_b32_e32 v43, v41
	v_or_b32_e32 v102, 25, v33
	v_lshlrev_b64 v[10:11], 5, v[42:43]
	v_lshl_add_u64 v[10:11], s[2:3], 0, v[10:11]
	v_or_b32_e32 v38, s4, v102
	v_mov_b32_e32 v39, v41
	v_or_b32_e32 v101, 26, v33
	global_load_dword v67, v[10:11], off
	v_lshlrev_b64 v[10:11], 5, v[38:39]
	v_lshl_add_u64 v[10:11], s[2:3], 0, v[10:11]
	v_or_b32_e32 v36, s4, v101
	v_mov_b32_e32 v37, v41
	global_load_dword v68, v[10:11], off
	v_or_b32_e32 v100, 27, v33
	v_lshlrev_b64 v[10:11], 5, v[36:37]
	v_lshl_add_u64 v[10:11], s[2:3], 0, v[10:11]
	v_or_b32_e32 v34, s4, v100
	v_mov_b32_e32 v35, v41
	global_load_dword v69, v[10:11], off
	v_lshlrev_b64 v[10:11], 5, v[34:35]
	v_lshl_add_u64 v[10:11], s[2:3], 0, v[10:11]
	global_load_dword v70, v[10:11], off
	v_or_b32_e32 v71, 0x60, v1
	v_and_b32_e32 v1, 64, v182
	v_xor_b32_e32 v22, 32, v182
	v_add_u32_e32 v74, 64, v1
	v_cmp_lt_i32_e32 vcc, v22, v74
	v_max_u32_e32 v73, 0x70, v71
	v_mov_b32_e32 v72, 0xf149f2ca
	v_cndmask_b32_e32 v22, v182, v22, vcc
	v_lshlrev_b32_e32 v109, 2, v22
	v_lshlrev_b32_e32 v22, 1, v32
	v_or_b32_e32 v108, 1, v33
	s_waitcnt vmcnt(13)
	v_mfma_f32_32x32x16_bf16 v[2:17], v[6:9], v[2:5], 0
	s_mov_b64 s[6:7], 0x5200000
	v_or_b32_e32 v84, s4, v33
	v_mov_b32_e32 v85, v41
	v_or_b32_e32 v78, s4, v108
	v_mov_b32_e32 v79, v41
	v_lshlrev_b64 v[82:83], 10, v[78:79]
	s_mov_b32 s2, 0xf149f2ca
	s_waitcnt vmcnt(11)
	v_mfma_f32_32x32x16_bf16 v[2:17], v[50:53], v[24:27], v[2:17]
	v_or_b32_e32 v26, 0x70, v33
	v_or_b32_e32 v27, 0x71, v33
	v_cmp_le_u32_e32 vcc, v26, v73
	v_or_b32_e32 v50, 0x72, v33
	v_lshl_add_u64 v[24:25], s[72:73], 0, v[22:23]
	v_lshl_add_u64 v[24:25], v[24:25], 0, s[0:1]
	v_or_b32_e32 v51, 0x73, v33
	s_waitcnt vmcnt(10)
	v_mfma_f32_32x32x16_bf16 v[2:17], v[54:57], v[28:31], v[2:17]
	s_waitcnt vmcnt(8)
	v_sub_f32_e32 v28, v62, v63
	s_waitcnt vmcnt(7)
	v_sub_f32_e32 v29, v62, v64
	s_waitcnt vmcnt(6)
	v_sub_f32_e32 v30, v62, v65
	v_or_b32_e32 v123, 2, v33
	v_or_b32_e32 v124, 3, v33
	v_or_b32_e32 v127, 8, v33
	v_or_b32_e32 v128, 9, v33
	s_waitcnt vmcnt(5)
	v_mfma_f32_32x32x16_bf16 v[2:17], v[18:21], v[58:61], v[2:17]
	v_or_b32_e32 v96, s4, v123
	v_mov_b32_e32 v97, v41
	v_or_b32_e32 v92, s4, v124
	v_mov_b32_e32 v93, v41
	v_or_b32_e32 v88, s4, v127
	v_mov_b32_e32 v89, v41
	v_or_b32_e32 v76, s4, v128
	s_nop 4
	v_add_f32_e32 v2, v10, v28
	v_add_f32_e32 v3, v11, v29
	v_cndmask_b32_e32 v10, v72, v2, vcc
	v_cmp_ge_u32_e32 vcc, v71, v27
	v_add_f32_e32 v4, v12, v30
	v_mov_b32_e32 v77, v41
	v_cndmask_b32_e32 v11, v72, v3, vcc
	v_cmp_ge_u32_e32 vcc, v71, v50
	v_lshlrev_b64 v[2:3], 10, v[84:85]
	v_max3_f32 v18, v10, s2, v11
	v_cndmask_b32_e32 v12, v72, v4, vcc
	v_lshl_add_u64 v[4:5], v[24:25], 0, s[6:7]
	v_lshl_add_u64 v[6:7], v[4:5], 0, v[2:3]
	v_lshl_add_u64 v[8:9], v[4:5], 0, v[82:83]
	global_load_ushort v28, v[6:7], off
	global_load_ushort v118, v[6:7], off offset:64
	global_load_ushort v29, v[8:9], off
	s_waitcnt vmcnt(7)
	v_sub_f32_e32 v6, v62, v66
	v_add_f32_e32 v6, v13, v6
	v_cmp_ge_u32_e32 vcc, v71, v51
	v_or_b32_e32 v13, 0x78, v33
	v_or_b32_e32 v135, 10, v33
	v_cndmask_b32_e32 v6, v72, v6, vcc
	v_max3_f32 v7, v18, v12, v6
	s_waitcnt vmcnt(6)
	v_sub_f32_e32 v18, v62, v67
	v_add_f32_e32 v14, v14, v18
	v_cmp_ge_u32_e32 vcc, v71, v13
	s_waitcnt vmcnt(5)
	v_sub_f32_e32 v18, v62, v68
	v_add_f32_e32 v15, v15, v18
	v_cndmask_b32_e32 v13, v72, v14, vcc
	v_or_b32_e32 v14, 0x79, v33
	v_cmp_ge_u32_e32 vcc, v71, v14
	s_waitcnt vmcnt(4)
	v_sub_f32_e32 v18, v62, v69
	v_add_f32_e32 v16, v16, v18
	v_cndmask_b32_e32 v14, v72, v15, vcc
	v_or_b32_e32 v15, 0x7a, v33
	v_cmp_ge_u32_e32 vcc, v71, v15
	s_waitcnt vmcnt(3)
	v_sub_f32_e32 v18, v62, v70
	v_add_f32_e32 v17, v17, v18
	v_cndmask_b32_e32 v15, v72, v16, vcc
	v_or_b32_e32 v16, 0x7b, v33
	v_cmp_ge_u32_e32 vcc, v71, v16
	v_max3_f32 v7, v7, v13, v14
	v_or_b32_e32 v136, 11, v33
	v_cndmask_b32_e32 v16, v72, v17, vcc
	v_max3_f32 v7, v7, v15, v16
	ds_bpermute_b32 v17, v109, v7
	v_lshlrev_b64 v[98:99], 10, v[96:97]
	v_lshlrev_b64 v[94:95], 10, v[92:93]
	v_lshlrev_b64 v[90:91], 10, v[88:89]
	v_lshlrev_b64 v[86:87], 10, v[76:77]
	s_waitcnt lgkmcnt(0)
	v_max3_f32 v7, v7, v17, s2
	v_sub_f32_e32 v10, v10, v7
	v_exp_f32_e32 v30, v10
	v_sub_f32_e32 v10, v11, v7
	v_exp_f32_e32 v31, v10
	v_sub_f32_e32 v10, v12, v7
	v_exp_f32_e32 v32, v10
	v_sub_f32_e32 v10, v13, v7
	v_sub_f32_e32 v17, 0xf149f2ca, v7
	v_exp_f32_e32 v115, v10
	v_sub_f32_e32 v10, v14, v7
	v_exp_f32_e32 v122, v17
	v_or_b32_e32 v17, v1, v33
	v_exp_f32_e32 v116, v10
	v_sub_f32_e32 v10, v15, v7
	v_or_b32_e32 v74, s4, v135
	v_mov_b32_e32 v75, v41
	v_or_b32_e32 v68, s4, v136
	v_mov_b32_e32 v69, v41
	v_sub_f32_e32 v6, v6, v7
	v_exp_f32_e32 v117, v10
	v_sub_f32_e32 v7, v16, v7
	v_lshlrev_b32_e32 v126, 2, v17
	v_lshl_add_u64 v[10:11], v[4:5], 0, v[98:99]
	v_lshl_add_u64 v[12:13], v[4:5], 0, v[94:95]
	v_lshl_add_u64 v[14:15], v[4:5], 0, v[90:91]
	v_lshl_add_u64 v[16:17], v[4:5], 0, v[86:87]
	global_load_ushort v129, v[8:9], off offset:64
	global_load_ushort v120, v[10:11], off
	global_load_ushort v130, v[10:11], off offset:64
	global_load_ushort v121, v[12:13], off
	global_load_ushort v131, v[12:13], off offset:64
	global_load_ushort v132, v[14:15], off
	global_load_ushort v133, v[14:15], off offset:64
	global_load_ushort v134, v[16:17], off
	v_lshlrev_b64 v[80:81], 10, v[74:75]
	v_lshlrev_b64 v[72:73], 10, v[68:69]
	v_lshl_add_u64 v[8:9], v[4:5], 0, v[80:81]
	v_lshl_add_u64 v[10:11], v[4:5], 0, v[72:73]
	global_load_ushort v137, v[16:17], off offset:64
	global_load_ushort v33, v[8:9], off
	global_load_ushort v138, v[8:9], off offset:64
	global_load_ushort v139, v[10:11], off
	global_load_ushort v140, v[10:11], off offset:64
	v_lshlrev_b64 v[52:53], 10, v[36:37]
	v_lshlrev_b64 v[70:71], 10, v[40:41]
	v_lshlrev_b64 v[66:67], 10, v[48:49]
	v_lshlrev_b64 v[64:65], 10, v[44:45]
	v_lshlrev_b64 v[60:61], 10, v[46:47]
	v_lshlrev_b64 v[58:59], 10, v[42:43]
	v_lshlrev_b64 v[54:55], 10, v[38:39]
	v_lshl_add_u64 v[26:27], v[4:5], 0, v[52:53]
	v_lshlrev_b64 v[50:51], 10, v[34:35]
	v_lshl_add_u64 v[8:9], v[4:5], 0, v[70:71]
	v_lshl_add_u64 v[10:11], v[4:5], 0, v[66:67]
	v_lshl_add_u64 v[12:13], v[4:5], 0, v[64:65]
	v_lshl_add_u64 v[14:15], v[4:5], 0, v[60:61]
	v_lshl_add_u64 v[16:17], v[4:5], 0, v[58:59]
	v_lshl_add_u64 v[24:25], v[4:5], 0, v[54:55]
	v_lshl_add_u64 v[4:5], v[4:5], 0, v[50:51]
	global_load_ushort v141, v[26:27], off
	global_load_ushort v142, v[4:5], off
	global_load_ushort v143, v[10:11], off offset:64
	global_load_ushort v144, v[12:13], off
	global_load_ushort v145, v[12:13], off offset:64
	global_load_ushort v146, v[14:15], off
	global_load_ushort v147, v[14:15], off offset:64
	global_load_ushort v148, v[16:17], off
	global_load_ushort v149, v[16:17], off offset:64
	global_load_ushort v150, v[24:25], off
	global_load_ushort v151, v[8:9], off
	global_load_ushort v152, v[8:9], off offset:64
	global_load_ushort v153, v[10:11], off
	global_load_ushort v154, v[24:25], off offset:64
	global_load_ushort v155, v[26:27], off offset:64
	global_load_ushort v156, v[4:5], off offset:64
	s_add_u32 s0, s72, s0
	s_addc_u32 s1, s73, 0
	v_lshl_add_u64 v[62:63], s[0:1], 0, v[22:23]
	s_mov_b64 s[0:1], 0x6300000
	v_lshl_add_u64 v[56:57], v[62:63], 0, s[0:1]
	v_lshl_add_u64 v[2:3], v[56:57], 0, v[2:3]
	global_load_ushort v157, v[2:3], off
	global_load_ushort v158, v[2:3], off offset:64
	v_add_f32_e32 v18, 0, v122
	v_add_f32_e32 v18, v122, v18
	v_add_f32_e32 v18, v122, v18
	v_add_f32_e32 v18, v122, v18
	v_add_f32_e32 v18, v122, v18
	v_add_f32_e32 v18, v122, v18
	v_add_f32_e32 v18, v122, v18
	v_add_f32_e32 v18, v122, v18
	v_exp_f32_e32 v114, v6
	v_add_f32_e32 v6, v30, v18
	ds_bpermute_b32 v18, v126, v122
	ds_bpermute_b32 v19, v126, v122 offset:4
	v_add_f32_e32 v6, v31, v6
	v_add_f32_e32 v6, v32, v6
	v_add_f32_e32 v6, v114, v6
	v_exp_f32_e32 v119, v7
	v_add_f32_e32 v6, v115, v6
	ds_bpermute_b32 v20, v126, v122 offset:8
	ds_bpermute_b32 v21, v126, v122 offset:12
	ds_bpermute_b32 v4, v126, v122 offset:40
	ds_bpermute_b32 v8, v126, v122 offset:64
	ds_bpermute_b32 v10, v126, v122 offset:72
	ds_bpermute_b32 v12, v126, v122 offset:96
	ds_bpermute_b32 v14, v126, v122 offset:104
	ds_bpermute_b32 v15, v126, v122 offset:108
	ds_bpermute_b32 v13, v126, v122 offset:100
	ds_bpermute_b32 v11, v126, v122 offset:76
	ds_bpermute_b32 v9, v126, v122 offset:68
	ds_bpermute_b32 v5, v126, v122 offset:44
	s_waitcnt lgkmcnt(12)
	v_pk_mul_f32 v[2:3], v[18:19], 0 op_sel_hi:[1,0]
	v_bfe_u32 v18, v122, 16, 1
	s_movk_i32 s0, 0x7fff
	v_add_f32_e32 v6, v116, v6
	v_add3_u32 v18, v122, v18, s0
	v_add_f32_e32 v6, v117, v6
	v_lshrrev_b32_e32 v19, 16, v18
	s_mov_b32 s1, 0xffff0000
	v_add_f32_e32 v125, v119, v6
	ds_bpermute_b32 v6, v126, v122 offset:32
	ds_bpermute_b32 v7, v126, v122 offset:36
	v_and_or_b32 v110, v18, s1, v19
	v_mov_b32_e32 v111, v110
	v_mov_b32_e32 v112, v110
	v_mov_b32_e32 v113, v110
	s_waitcnt lgkmcnt(6)
	v_pk_mul_f32 v[16:17], v[14:15], 0 op_sel_hi:[1,0]
	s_waitcnt lgkmcnt(5)
	v_pk_mul_f32 v[14:15], v[12:13], 0 op_sel_hi:[1,0]
	s_waitcnt lgkmcnt(4)
	v_pk_mul_f32 v[12:13], v[10:11], 0 op_sel_hi:[1,0]
	s_waitcnt lgkmcnt(3)
	v_pk_mul_f32 v[10:11], v[8:9], 0 op_sel_hi:[1,0]
	s_waitcnt lgkmcnt(2)
	v_pk_mul_f32 v[8:9], v[4:5], 0 op_sel_hi:[1,0]
	v_pk_mul_f32 v[4:5], v[20:21], 0 op_sel_hi:[1,0]
	v_bfe_u32 v21, v31, 16, 1
	v_bfe_u32 v18, v119, 16, 1
	v_bfe_u32 v19, v116, 16, 1
	v_bfe_u32 v20, v114, 16, 1
	v_add3_u32 v159, v31, v21, s0
	v_bfe_u32 v21, v117, 16, 1
	v_fmac_f32_e32 v125, 0, v122
	v_add3_u32 v160, v114, v20, s0
	v_add3_u32 v161, v116, v19, s0
	v_add3_u32 v119, v119, v18, s0
	v_bfe_u32 v18, v30, 16, 1
	v_bfe_u32 v19, v32, 16, 1
	v_bfe_u32 v20, v115, 16, 1
	v_add3_u32 v21, v117, v21, s0
	s_mov_b32 s4, 0x5040100
	ds_bpermute_b32 v109, v109, v125
	s_waitcnt lgkmcnt(1)
	v_pk_mul_f32 v[6:7], v[6:7], 0 op_sel_hi:[1,0]
	v_add3_u32 v20, v115, v20, s0
	v_add3_u32 v19, v32, v19, s0
	v_add3_u32 v18, v30, v18, s0
	v_lshrrev_b32_e32 v165, 16, v21
	s_waitcnt vmcnt(19)
	v_perm_b32 v117, v139, v33, s4
	v_perm_b32 v116, v134, v132, s4
	v_perm_b32 v115, v121, v120, s4
	v_perm_b32 v114, v29, v28, s4
	v_lshrrev_b32_e32 v162, 16, v18
	v_lshrrev_b32_e32 v163, 16, v19
	v_lshrrev_b32_e32 v164, 16, v20
	v_mfma_f32_32x32x16_bf16 v[18:33], v[110:113], v[114:117], v[2:17]
	v_and_or_b32 v117, v119, s1, v165
	s_waitcnt vmcnt(18)
	v_perm_b32 v121, v140, v138, s4
	v_perm_b32 v120, v137, v133, s4
	v_perm_b32 v119, v131, v130, s4
	v_perm_b32 v118, v129, v118, s4
	v_and_or_b32 v116, v161, s1, v164
	v_and_or_b32 v115, v160, s1, v163
	v_mfma_f32_32x32x16_bf16 v[2:17], v[110:113], v[118:121], v[2:17]
	v_and_or_b32 v114, v159, s1, v162
	s_waitcnt lgkmcnt(0)
	v_add_f32_e32 v109, v125, v109
	v_div_scale_f32 v118, s[2:3], v109, v109, 1.0
	v_rcp_f32_e32 v119, v118
	s_waitcnt vmcnt(16)
	v_perm_b32 v113, v142, v141, s4
	s_waitcnt vmcnt(8)
	v_perm_b32 v112, v150, v148, s4
	v_perm_b32 v111, v146, v144, s4
	s_waitcnt vmcnt(5)
	v_perm_b32 v110, v153, v151, s4
	s_mov_b64 s[2:3], 0x10000000
	v_lshl_add_u64 v[62:63], v[62:63], 0, s[2:3]
	v_mfma_f32_32x32x16_bf16 v[18:33], v[114:117], v[110:113], v[18:33]
	s_waitcnt vmcnt(2)
	v_perm_b32 v113, v156, v155, s4
	v_perm_b32 v112, v154, v149, s4
	v_perm_b32 v111, v147, v145, s4
	v_perm_b32 v110, v143, v152, s4
	v_lshlrev_b64 v[84:85], 11, v[84:85]
	v_lshl_add_u64 v[84:85], v[62:63], 0, v[84:85]
	v_lshl_add_u64 v[82:83], v[56:57], 0, v[82:83]
	v_mfma_f32_32x32x16_bf16 v[2:17], v[114:117], v[110:113], v[2:17]
	v_fma_f32 v110, -v118, v119, 1.0
	v_fmac_f32_e32 v119, v110, v119
	v_div_scale_f32 v110, vcc, 1.0, v109, 1.0
	v_mul_f32_e32 v111, v110, v119
	v_fma_f32 v112, -v118, v111, v110
	v_fmac_f32_e32 v111, v112, v119
	v_fma_f32 v110, -v118, v111, v110
	v_div_fmas_f32 v110, v110, v119, v111
	v_div_fixup_f32 v109, v110, v109, 1.0
	ds_bpermute_b32 v110, v126, v109
	s_waitcnt vmcnt(1)
	v_lshlrev_b32_e32 v111, 16, v157
	s_waitcnt vmcnt(0)
	v_lshlrev_b32_e32 v112, 16, v158
	s_waitcnt lgkmcnt(0)
	v_mul_f32_e32 v18, v18, v110
	v_mul_f32_e32 v18, v18, v111
	v_bfe_u32 v111, v18, 16, 1
	v_mul_f32_e32 v2, v2, v110
	v_add3_u32 v18, v18, v111, s0
	v_mul_f32_e32 v2, v2, v112
	global_store_short_d16_hi v[84:85], v18, off
	v_bfe_u32 v18, v2, 16, 1
	v_add3_u32 v2, v2, v18, s0
	global_store_short_d16_hi v[84:85], v2, off offset:64
	global_load_ushort v2, v[82:83], off
	s_nop 0
	global_load_ushort v18, v[82:83], off offset:64
	v_or_b32_e32 v82, v1, v108
	v_lshlrev_b32_e32 v82, 2, v82
	ds_bpermute_b32 v82, v82, v109
	s_waitcnt vmcnt(1)
	v_lshlrev_b32_e32 v2, 16, v2
	s_waitcnt vmcnt(0)
	v_lshlrev_b32_e32 v83, 16, v18
	s_waitcnt lgkmcnt(0)
	v_mul_f32_e32 v18, v19, v82
	v_mul_f32_e32 v2, v18, v2
	v_bfe_u32 v18, v2, 16, 1
	v_add3_u32 v2, v2, v18, s0
	v_lshlrev_b64 v[18:19], 11, v[78:79]
	v_lshl_add_u64 v[18:19], v[62:63], 0, v[18:19]
	global_store_short_d16_hi v[18:19], v2, off
	v_mul_f32_e32 v2, v3, v82
	v_mul_f32_e32 v2, v2, v83
	v_bfe_u32 v3, v2, 16, 1
	v_add3_u32 v2, v2, v3, s0
	global_store_short_d16_hi v[18:19], v2, off offset:64
	v_lshl_add_u64 v[2:3], v[56:57], 0, v[98:99]
	global_load_ushort v18, v[2:3], off
	global_load_ushort v19, v[2:3], off offset:64
	v_or_b32_e32 v2, v1, v123
	v_lshlrev_b32_e32 v2, 2, v2
	ds_bpermute_b32 v78, v2, v109
	s_waitcnt lgkmcnt(0)
	v_mul_f32_e32 v3, v20, v78
	v_mul_f32_e32 v4, v4, v78
	s_waitcnt vmcnt(1)
	v_lshlrev_b32_e32 v2, 16, v18
	s_waitcnt vmcnt(0)
	v_lshlrev_b32_e32 v18, 16, v19
	v_mul_f32_e32 v2, v3, v2
	v_bfe_u32 v3, v2, 16, 1
	v_mul_f32_e32 v4, v4, v18
	v_add3_u32 v19, v2, v3, s0
	v_lshlrev_b64 v[2:3], 11, v[96:97]
	v_bfe_u32 v18, v4, 16, 1
	v_lshl_add_u64 v[2:3], v[62:63], 0, v[2:3]
	v_add3_u32 v4, v4, v18, s0
	global_store_short_d16_hi v[2:3], v19, off
	global_store_short_d16_hi v[2:3], v4, off offset:64
	v_lshl_add_u64 v[2:3], v[56:57], 0, v[94:95]
	global_load_ushort v4, v[2:3], off
	global_load_ushort v18, v[2:3], off offset:64
	v_or_b32_e32 v2, v1, v124
	v_lshlrev_b32_e32 v2, 2, v2
	ds_bpermute_b32 v19, v2, v109
	s_waitcnt lgkmcnt(0)
	v_mul_f32_e32 v3, v21, v19
	v_mul_f32_e32 v5, v5, v19
	s_waitcnt vmcnt(1)
	v_lshlrev_b32_e32 v2, 16, v4
	s_waitcnt vmcnt(0)
	v_lshlrev_b32_e32 v4, 16, v18
	v_mul_f32_e32 v2, v3, v2
	v_bfe_u32 v3, v2, 16, 1
	v_mul_f32_e32 v4, v5, v4
	v_add3_u32 v18, v2, v3, s0
	v_lshlrev_b64 v[2:3], 11, v[92:93]
	v_bfe_u32 v5, v4, 16, 1
	v_lshl_add_u64 v[2:3], v[62:63], 0, v[2:3]
	v_add3_u32 v4, v4, v5, s0
	global_store_short_d16_hi v[2:3], v18, off
	global_store_short_d16_hi v[2:3], v4, off offset:64
	v_lshl_add_u64 v[2:3], v[56:57], 0, v[90:91]
	global_load_ushort v18, v[2:3], off
	global_load_ushort v19, v[2:3], off offset:64
	v_or_b32_e32 v2, v1, v127
	v_lshlrev_b32_e32 v2, 2, v2
	ds_bpermute_b32 v20, v2, v109
	v_lshlrev_b64 v[2:3], 11, v[88:89]
	v_lshl_add_u64 v[2:3], v[62:63], 0, v[2:3]
	v_lshl_add_u64 v[4:5], v[56:57], 0, v[86:87]
	s_waitcnt lgkmcnt(0)
	v_mul_f32_e32 v21, v22, v20
	v_mul_f32_e32 v6, v6, v20
	s_waitcnt vmcnt(1)
	v_lshlrev_b32_e32 v18, 16, v18
	s_waitcnt vmcnt(0)
	v_lshlrev_b32_e32 v19, 16, v19
	v_mul_f32_e32 v18, v21, v18
	v_mul_f32_e32 v6, v6, v19
	v_bfe_u32 v19, v18, 16, 1
	v_bfe_u32 v20, v6, 16, 1
	v_add3_u32 v18, v18, v19, s0
	v_add3_u32 v6, v6, v20, s0
	global_store_short_d16_hi v[2:3], v18, off
	global_store_short_d16_hi v[2:3], v6, off offset:64
	global_load_ushort v6, v[4:5], off
	s_nop 0
	global_load_ushort v18, v[4:5], off offset:64
	v_or_b32_e32 v2, v1, v128
	v_lshlrev_b32_e32 v2, 2, v2
	ds_bpermute_b32 v19, v2, v109
	v_lshlrev_b64 v[2:3], 11, v[76:77]
	v_lshl_add_u64 v[2:3], v[62:63], 0, v[2:3]
	v_lshl_add_u64 v[4:5], v[56:57], 0, v[80:81]
	s_waitcnt lgkmcnt(0)
	v_mul_f32_e32 v20, v23, v19
	v_mul_f32_e32 v7, v7, v19
	s_waitcnt vmcnt(1)
	v_lshlrev_b32_e32 v6, 16, v6
	s_waitcnt vmcnt(0)
	v_lshlrev_b32_e32 v18, 16, v18
	v_mul_f32_e32 v6, v20, v6
	v_mul_f32_e32 v7, v7, v18
	v_bfe_u32 v18, v6, 16, 1
	v_bfe_u32 v19, v7, 16, 1
	v_add3_u32 v6, v6, v18, s0
	v_add3_u32 v7, v7, v19, s0
	global_store_short_d16_hi v[2:3], v6, off
	global_store_short_d16_hi v[2:3], v7, off offset:64
	global_load_ushort v6, v[4:5], off
	s_nop 0
	global_load_ushort v7, v[4:5], off offset:64
	v_or_b32_e32 v2, v1, v135
	v_lshlrev_b32_e32 v2, 2, v2
	ds_bpermute_b32 v18, v2, v109
	v_lshlrev_b64 v[2:3], 11, v[74:75]
	v_lshl_add_u64 v[2:3], v[62:63], 0, v[2:3]
	v_lshl_add_u64 v[4:5], v[56:57], 0, v[72:73]
	s_waitcnt lgkmcnt(0)
	v_mul_f32_e32 v19, v24, v18
	v_mul_f32_e32 v8, v8, v18
	s_waitcnt vmcnt(1)
	v_lshlrev_b32_e32 v6, 16, v6
	s_waitcnt vmcnt(0)
	v_lshlrev_b32_e32 v7, 16, v7
	v_mul_f32_e32 v6, v19, v6
	v_mul_f32_e32 v7, v8, v7
	v_bfe_u32 v8, v6, 16, 1
	v_bfe_u32 v18, v7, 16, 1
	v_add3_u32 v6, v6, v8, s0
	v_add3_u32 v7, v7, v18, s0
	global_store_short_d16_hi v[2:3], v6, off
	global_store_short_d16_hi v[2:3], v7, off offset:64
	global_load_ushort v6, v[4:5], off
	s_nop 0
	global_load_ushort v7, v[4:5], off offset:64
	v_or_b32_e32 v2, v1, v136
	v_lshlrev_b32_e32 v2, 2, v2
	ds_bpermute_b32 v8, v2, v109
	v_lshlrev_b64 v[2:3], 11, v[68:69]
	v_lshl_add_u64 v[2:3], v[62:63], 0, v[2:3]
	v_lshl_add_u64 v[4:5], v[56:57], 0, v[70:71]
	s_waitcnt lgkmcnt(0)
	v_mul_f32_e32 v18, v25, v8
	v_mul_f32_e32 v8, v9, v8
	s_waitcnt vmcnt(1)
	v_lshlrev_b32_e32 v6, 16, v6
	s_waitcnt vmcnt(0)
	v_lshlrev_b32_e32 v7, 16, v7
	v_mul_f32_e32 v6, v18, v6
	v_mul_f32_e32 v7, v8, v7
	v_bfe_u32 v8, v6, 16, 1
	v_bfe_u32 v9, v7, 16, 1
	v_add3_u32 v6, v6, v8, s0
	v_add3_u32 v7, v7, v9, s0
	global_store_short_d16_hi v[2:3], v6, off
	global_store_short_d16_hi v[2:3], v7, off offset:64
	global_load_ushort v6, v[4:5], off
	s_nop 0
	global_load_ushort v7, v[4:5], off offset:64
	v_or_b32_e32 v2, v1, v107
	v_lshlrev_b32_e32 v2, 2, v2
	ds_bpermute_b32 v8, v2, v109
	v_lshlrev_b64 v[2:3], 11, v[40:41]
	v_lshl_add_u64 v[2:3], v[62:63], 0, v[2:3]
	v_lshl_add_u64 v[4:5], v[56:57], 0, v[66:67]
	s_waitcnt lgkmcnt(0)
	v_mul_f32_e32 v9, v26, v8
	v_mul_f32_e32 v8, v10, v8
	s_waitcnt vmcnt(1)
	v_lshlrev_b32_e32 v6, 16, v6
	s_waitcnt vmcnt(0)
	v_lshlrev_b32_e32 v7, 16, v7
	v_mul_f32_e32 v6, v9, v6
	v_mul_f32_e32 v7, v8, v7
	v_bfe_u32 v8, v6, 16, 1
	v_bfe_u32 v9, v7, 16, 1
	v_add3_u32 v6, v6, v8, s0
	v_add3_u32 v7, v7, v9, s0
	global_store_short_d16_hi v[2:3], v6, off
	global_store_short_d16_hi v[2:3], v7, off offset:64
	global_load_ushort v6, v[4:5], off
	s_nop 0
	global_load_ushort v7, v[4:5], off offset:64
	v_or_b32_e32 v2, v1, v106
	v_lshlrev_b32_e32 v2, 2, v2
	ds_bpermute_b32 v8, v2, v109
	v_lshlrev_b64 v[2:3], 11, v[48:49]
	v_lshl_add_u64 v[2:3], v[62:63], 0, v[2:3]
	v_lshl_add_u64 v[4:5], v[56:57], 0, v[64:65]
	s_waitcnt lgkmcnt(0)
	v_mul_f32_e32 v9, v27, v8
	v_mul_f32_e32 v8, v11, v8
	s_waitcnt vmcnt(1)
	v_lshlrev_b32_e32 v6, 16, v6
	s_waitcnt vmcnt(0)
	v_lshlrev_b32_e32 v7, 16, v7
	v_mul_f32_e32 v6, v9, v6
	v_mul_f32_e32 v7, v8, v7
	v_bfe_u32 v8, v6, 16, 1
	v_bfe_u32 v9, v7, 16, 1
	v_add3_u32 v6, v6, v8, s0
	v_add3_u32 v7, v7, v9, s0
	global_store_short_d16_hi v[2:3], v6, off
	global_store_short_d16_hi v[2:3], v7, off offset:64
	global_load_ushort v6, v[4:5], off
	s_nop 0
	global_load_ushort v7, v[4:5], off offset:64
	v_or_b32_e32 v2, v1, v105
	v_lshlrev_b32_e32 v2, 2, v2
	ds_bpermute_b32 v8, v2, v109
	v_lshlrev_b64 v[2:3], 11, v[44:45]
	v_lshl_add_u64 v[2:3], v[62:63], 0, v[2:3]
	v_lshl_add_u64 v[4:5], v[56:57], 0, v[60:61]
	s_waitcnt lgkmcnt(0)
	v_mul_f32_e32 v9, v28, v8
	v_mul_f32_e32 v8, v12, v8
	s_waitcnt vmcnt(1)
	v_lshlrev_b32_e32 v6, 16, v6
	s_waitcnt vmcnt(0)
	v_lshlrev_b32_e32 v7, 16, v7
	v_mul_f32_e32 v6, v9, v6
	v_mul_f32_e32 v7, v8, v7
	v_bfe_u32 v8, v6, 16, 1
	v_bfe_u32 v9, v7, 16, 1
	v_add3_u32 v6, v6, v8, s0
	v_add3_u32 v7, v7, v9, s0
	global_store_short_d16_hi v[2:3], v6, off
	global_store_short_d16_hi v[2:3], v7, off offset:64
	global_load_ushort v6, v[4:5], off
	s_nop 0
	global_load_ushort v7, v[4:5], off offset:64
	v_or_b32_e32 v2, v1, v104
	v_lshlrev_b32_e32 v2, 2, v2
	ds_bpermute_b32 v8, v2, v109
	v_lshlrev_b64 v[2:3], 11, v[46:47]
	v_lshl_add_u64 v[2:3], v[62:63], 0, v[2:3]
	v_lshl_add_u64 v[4:5], v[56:57], 0, v[58:59]
	s_waitcnt lgkmcnt(0)
	v_mul_f32_e32 v9, v29, v8
	v_mul_f32_e32 v8, v13, v8
	s_waitcnt vmcnt(1)
	v_lshlrev_b32_e32 v6, 16, v6
	s_waitcnt vmcnt(0)
	v_lshlrev_b32_e32 v7, 16, v7
	v_mul_f32_e32 v6, v9, v6
	v_mul_f32_e32 v7, v8, v7
	v_bfe_u32 v8, v6, 16, 1
	v_bfe_u32 v9, v7, 16, 1
	v_add3_u32 v6, v6, v8, s0
	v_add3_u32 v7, v7, v9, s0
	global_store_short_d16_hi v[2:3], v6, off
	global_store_short_d16_hi v[2:3], v7, off offset:64
	global_load_ushort v6, v[4:5], off
	s_nop 0
	global_load_ushort v7, v[4:5], off offset:64
	v_or_b32_e32 v2, v1, v103
	v_lshlrev_b32_e32 v2, 2, v2
	ds_bpermute_b32 v8, v2, v109
	v_lshlrev_b64 v[2:3], 11, v[42:43]
	v_lshl_add_u64 v[2:3], v[62:63], 0, v[2:3]
	v_lshl_add_u64 v[4:5], v[56:57], 0, v[54:55]
	s_waitcnt lgkmcnt(0)
	v_mul_f32_e32 v9, v30, v8
	v_mul_f32_e32 v8, v14, v8
	s_waitcnt vmcnt(1)
	v_lshlrev_b32_e32 v6, 16, v6
	s_waitcnt vmcnt(0)
	v_lshlrev_b32_e32 v7, 16, v7
	v_mul_f32_e32 v6, v9, v6
	v_mul_f32_e32 v7, v8, v7
	v_bfe_u32 v8, v6, 16, 1
	v_bfe_u32 v9, v7, 16, 1
	v_add3_u32 v6, v6, v8, s0
	v_add3_u32 v7, v7, v9, s0
	global_store_short_d16_hi v[2:3], v6, off
	global_store_short_d16_hi v[2:3], v7, off offset:64
	global_load_ushort v6, v[4:5], off
	s_nop 0
	global_load_ushort v7, v[4:5], off offset:64
	v_or_b32_e32 v2, v1, v102
	v_lshlrev_b32_e32 v2, 2, v2
	ds_bpermute_b32 v8, v2, v109
	v_lshlrev_b64 v[2:3], 11, v[38:39]
	v_lshl_add_u64 v[2:3], v[62:63], 0, v[2:3]
	v_lshl_add_u64 v[4:5], v[56:57], 0, v[52:53]
	s_waitcnt lgkmcnt(0)
	v_mul_f32_e32 v9, v31, v8
	v_mul_f32_e32 v8, v15, v8
	s_waitcnt vmcnt(1)
	v_lshlrev_b32_e32 v6, 16, v6
	s_waitcnt vmcnt(0)
	v_lshlrev_b32_e32 v7, 16, v7
	v_mul_f32_e32 v6, v9, v6
	v_mul_f32_e32 v7, v8, v7
	v_bfe_u32 v8, v6, 16, 1
	v_bfe_u32 v9, v7, 16, 1
	v_add3_u32 v6, v6, v8, s0
	v_add3_u32 v7, v7, v9, s0
	global_store_short_d16_hi v[2:3], v6, off
	global_store_short_d16_hi v[2:3], v7, off offset:64
	global_load_ushort v6, v[4:5], off
	s_nop 0
	global_load_ushort v7, v[4:5], off offset:64
	v_or_b32_e32 v2, v1, v101
	v_lshlrev_b32_e32 v2, 2, v2
	ds_bpermute_b32 v8, v2, v109
	v_lshlrev_b64 v[2:3], 11, v[36:37]
	v_lshl_add_u64 v[2:3], v[62:63], 0, v[2:3]
	v_lshl_add_u64 v[4:5], v[56:57], 0, v[50:51]
	v_or_b32_e32 v1, v1, v100
	s_waitcnt lgkmcnt(0)
	v_mul_f32_e32 v9, v32, v8
	v_mul_f32_e32 v8, v16, v8
	v_lshlrev_b32_e32 v1, 2, v1
	ds_bpermute_b32 v1, v1, v109
	s_waitcnt vmcnt(1)
	v_lshlrev_b32_e32 v6, 16, v6
	s_waitcnt vmcnt(0)
	v_lshlrev_b32_e32 v7, 16, v7
	v_mul_f32_e32 v6, v9, v6
	v_mul_f32_e32 v7, v8, v7
	v_bfe_u32 v8, v6, 16, 1
	v_bfe_u32 v9, v7, 16, 1
	v_add3_u32 v6, v6, v8, s0
	v_add3_u32 v7, v7, v9, s0
	global_store_short_d16_hi v[2:3], v6, off
	global_store_short_d16_hi v[2:3], v7, off offset:64
	global_load_ushort v6, v[4:5], off
	s_nop 0
	global_load_ushort v7, v[4:5], off offset:64
	s_waitcnt lgkmcnt(0)
	v_mul_f32_e32 v4, v33, v1
	v_mul_f32_e32 v1, v17, v1
	v_lshlrev_b64 v[2:3], 11, v[34:35]
	v_lshl_add_u64 v[2:3], v[62:63], 0, v[2:3]
	s_waitcnt vmcnt(1)
	v_lshlrev_b32_e32 v5, 16, v6
	s_waitcnt vmcnt(0)
	v_lshlrev_b32_e32 v6, 16, v7
	v_mul_f32_e32 v4, v4, v5
	v_mul_f32_e32 v1, v1, v6
	v_bfe_u32 v5, v4, 16, 1
	v_bfe_u32 v6, v1, 16, 1
	v_add3_u32 v4, v4, v5, s0
	v_add3_u32 v1, v1, v6, s0
	global_store_short_d16_hi v[2:3], v4, off
	global_store_short_d16_hi v[2:3], v1, off offset:64
